# S2 + de-serialised NAT-QKV strip tail (stats and both bias loads issued together)
# baseline (speedup 1.0000x reference)
; #define PG8_LAS __attribute__((address_space(3)))
;     __device__ __forceinline__ void prefetch(const Unit& u, PG8_LAS float* area, int lane, int wr, int wc) const {
;     ...
;         const int vec = (u.pm % PTILES == 0) ? 2 : (u.pm / PTILES);
;         const gf32* sp = stats + u.pm * BM + wr * 64 + lane;
;     __device__ __forceinline__ void strip(const f32x4 (&accS)[2], const Unit& u, int wr, int wc, int fr, int fq) const {
;         asm volatile("" : "+v"(fr), "+v"(fq));
;         int colt = u.pn * BM; gb16* base = P0; int ldc = ld0; float qs = qscale;
;         if (colt >= n0 + n1) { base = P2; ldc = ld1; colt -= n0 + n1; qs = 1.f; } else if (colt >= n0) { base = P1; ldc = ld1; colt -= n0; qs = 1.f; }
;         const int row = u.srow + fr; const float rs = rstd_of(stats[row]);
;         gb16* rowp = base + (size_t)row * ldc + colt + wc * 32 + 8 * fq + 4 * wr; const gf32* bp = bias + (size_t)2 * nb + u.pn * BM + wc * 32 + 8 * fq + 4 * wr;
;         if (gk && base == P1) {
;             f32x4 v[2];
;             __builtin_amdgcn_s_barrier();
; #pragma unroll
;             for (int bj = 0; bj < 2; ++bj) { v[bj] = accS[bj] * rs + *(const gf32x4*)(bp + bj * HALF);
;                 float q = (v[bj].x * v[bj].x + v[bj].y * v[bj].y) + (v[bj].z * v[bj].z + v[bj].w * v[bj].w); q += __shfl_xor(q, 16); q += __shfl_xor(q, 32);
;                 if (fq == 0) xk[(bj * 16 + fr) * 8 + wr * 4 + wc] = q; }
;             asm volatile("s_waitcnt lgkmcnt(0)" ::: "memory"); __builtin_amdgcn_s_barrier(); asm volatile("" ::: "memory");
;             const f32x4 g = *(const gf32x4*)(gk + wc * 32 + 8 * fq + 4 * wr);
; #pragma unroll
;             for (int bj = 0; bj < 2; ++bj) { const f32x4 p0 = *(const PG8_LAS f32x4*)(xk + (bj * 16 + fr) * 8), p1 = *(const PG8_LAS f32x4*)(xk + (bj * 16 + fr) * 8 + 4);
;                 const float rh = __builtin_amdgcn_rsqf((((p0.x + p0.y) + (p0.z + p0.w)) + ((p1.x + p1.y) + (p1.z + p1.w))) * (1.0f / 128.0f) + NORM_EPS);
;                 const f32x4 y = v[bj] * rh * g; u32x2 w; w.x = cvt_pk_bf16(y[0], y[1]); w.y = cvt_pk_bf16(y[2], y[3]); *(gu32x2*)(rowp + bj * HALF) = w; }
;             return; }
; #pragma unroll
;         for (int bj = 0; bj < 2; ++bj) { const f32x4 v = (accS[bj] * rs + *(const gf32x4*)(bp + bj * HALF)) * qs; u32x2 w; w.x = cvt_pk_bf16(v[0], v[1]); w.y = cvt_pk_bf16(v[2], v[3]); *(gu32x2*)(rowp + bj * HALF) = w; }
.LBB0_561:
	v_add_u32_e32 v10, s4, v9
	v_readlane_b32 s22, v254, 48
	v_ashrrev_i32_e32 v11, 31, v10
	v_readlane_b32 s23, v254, 49
	s_ashr_i32 s41, s40, 31
	s_ashr_i32 s29, s28, 31
	v_lshl_add_u64 v[12:13], v[10:11], 2, s[22:23]
	global_load_dword v100, v[12:13], off
	v_lshlrev_b64 v[10:11], 12, v[10:11]
	v_lshl_add_u64 v[10:11], s[64:65], 0, v[10:11]
	s_lshl_b64 s[22:23], s[40:41], 2
	v_lshl_add_u64 v[10:11], s[28:29], 1, v[10:11]
	v_lshlrev_b32_e32 v8, 3, v8
	s_add_u32 s22, s96, s22
	v_lshl_add_u64 v[10:11], v[10:11], 0, s[48:49]
	s_addc_u32 s23, s97, s23
	s_and_b64 vcc, exec, s[38:39]
	v_ashrrev_i32_e32 v9, 31, v8
	v_lshl_add_u64 v[10:11], v[8:9], 1, v[10:11]
	v_lshl_add_u64 v[8:9], v[8:9], 2, s[22:23]
	v_lshl_add_u64 v[16:17], s[44:45], 2, v[8:9]
	v_lshl_add_u64 v[14:15], s[44:45], 1, v[10:11]
	global_load_dwordx4 v[104:107], v[16:17], off
	global_load_dwordx4 v[108:111], v[16:17], off offset:512
	s_waitcnt vmcnt(0)
	v_fmamk_f32 v9, v100, 0x3a000000, v240
	v_rsq_f32_e32 v12, v9
	s_nop 1
	v_pk_fma_f32 v[4:5], v[4:5], v[12:13], v[104:105] op_sel_hi:[1,0,1]
	v_pk_fma_f32 v[6:7], v[6:7], v[12:13], v[106:107] op_sel_hi:[1,0,1]
	v_pk_mul_f32 v[4:5], s[2:3], v[4:5] op_sel_hi:[0,1]
	v_pk_mul_f32 v[6:7], s[2:3], v[6:7] op_sel_hi:[0,1]
	v_cvt_pk_bf16_f32 v4, v4, v5
	v_cvt_pk_bf16_f32 v5, v6, v7
	s_nop 0
	global_store_dwordx2 v[14:15], v[4:5], off
	v_pk_fma_f32 v[0:1], v[0:1], v[12:13], v[108:109] op_sel_hi:[1,0,1]
	v_pk_fma_f32 v[2:3], v[2:3], v[12:13], v[110:111] op_sel_hi:[1,0,1]
	v_pk_mul_f32 v[0:1], s[2:3], v[0:1] op_sel_hi:[0,1]
	v_pk_mul_f32 v[2:3], s[2:3], v[2:3] op_sel_hi:[0,1]
	s_mov_b64 s[2:3], -1
	v_cvt_pk_bf16_f32 v0, v0, v1
	v_cvt_pk_bf16_f32 v1, v2, v3
	s_nop 0
	global_store_dwordx2 v[14:15], v[0:1], off offset:256
	s_cbranch_vccnz .LBB0_530
	s_mul_hi_i32 s2, s54, 0x78787879
	s_lshr_b32 s3, s2, 31
	s_ashr_i32 s2, s2, 3
	s_add_i32 s2, s2, s3
	s_mul_i32 s3, s2, 17
	s_sub_i32 s3, s54, s3
	v_mov_b32_e32 v0, v230
	s_cmp_eq_u32 s3, 0
	s_cbranch_scc1 .LBB0_564
	s_mul_hi_i32 s3, s2, 0x1800
	s_mulk_i32 s2, 0x1800
	s_branch .LBB0_565
